# grid barriers: early L2 write-back by the 29th arriver of an XCD; phase 1: the 260 tiles of the 9th round spread over all eight XCDs, one workgroup per CU
# speedup vs baseline: 1.0438x; 1.0023x over previous
; DI unsigned xb_add(unsigned* p, unsigned v) { return __hip_atomic_fetch_add(p, v, __ATOMIC_RELAXED, __HIP_MEMORY_SCOPE_AGENT); }
; DI void xcd_barrier(const XcdBarrier& b) {
;     ...
;         const unsigned old = xb_add(&bar[XB_XSUB(b.x)], 1u);
;         const unsigned gen = old / nloc;
;         if (old + 1u == (gen + 1u) * nloc) {
;             __builtin_amdgcn_fence(__ATOMIC_RELEASE, "agent");
.LBB0_60:
	s_or_b64 exec, exec, s[10:11]
	v_cvt_f32_u32_e32 v6, v4
	s_waitcnt vmcnt(0)
	v_readfirstlane_b32 s6, v5
	s_and_b32 s96, s6, 63
	s_cmp_lg_u32 s96, 28
	s_cbranch_scc1 .Lbw_0_0
	buffer_wbl2 sc1

; #define TILE_MN(t, M0, N0) do { int pan_ = (t) / (mtiles * 8); if (pan_ >= npan) pan_ = npan - 1; const int pw_ = (pan_ == npan - 1) ? ntiles - 8 * pan_ : 8; const int loc_ = (t) - pan_ * mtiles * 8; \
;         M0 = (loc_ / pw_) * 128; N0 = (8 * pan_ + loc_ % pw_) * 128; } while (0)
; template <class Epi>
; DI void gemm_phase(const u16* __restrict__ A, const u16* __restrict__ B, int mtiles, int ntiles, char* lds, const Epi& epi) {
;     ...
;         for (int i = 0; i < 4; ++i) { const int row = 8 * (i * 4 + wave) + (lane >> 3); const int ch = (lane & 7) ^ ((row >> 1) & 7); soff[i] = (unsigned)(row * 1024 + ch * 8); }
;         const u16* ga = A + (size_t)m0 * 1024; const u16* gb = B + (size_t)n0 * 1024;
;         __syncthreads();
;         for (int kt = 0; kt < 16; ++kt) {
;             if (kt + 1 < 16) GSTAGE((kt + 1) & 1, kt + 1, ga, gb);
;             const char* sa = lds + (kt & 1) * 32768; const char* sb = sa + 16384;
; #pragma unroll
;             for (int ks = 0; ks < 4; ++ks) {
;                 bf16x8 fw[2], fx[2];
; #pragma unroll
;                 for (int ct = 0; ct < 2; ++ct) fw[ct] = *(const bf16x8*)(sb + swz(wn * 64 + ct * 32 + r, 2 * ks + h));
; #pragma unroll
;                 for (int tt = 0; tt < 2; ++tt) fx[tt] = *(const bf16x8*)(sa + swz(wm * 64 + tt * 32 + r, 2 * ks + h));
; #pragma unroll
;                 for (int ct = 0; ct < 2; ++ct)
; #pragma unroll
;                     for (int tt = 0; tt < 2; ++tt) acc[ct][tt] = __builtin_amdgcn_mfma_f32_32x32x16_bf16(fw[ct], fx[tt], acc[ct][tt], 0, 0, 0);
;     ...
;         const int nxt = tile + (int)gridDim.x; int m1 = 0, n1 = 0;
;         if (nxt < ntile) { TILE_MN(nxt, m1, n1); GSTAGE(0, 0, A + (size_t)m1 * 1024, B + (size_t)n1 * 1024); }
.LBB0_97:
	v_mov_b32_e32 v18, v0
	s_ashr_i32 s83, s82, 31
	v_readfirstlane_b32 s1, v18
	s_ashr_i32 s7, s1, 6
	s_ashr_i32 s4, s1, 7
	s_and_b32 s6, s7, 1
	v_bfe_u32 v2, v18, 3, 3
	s_lshl_b64 s[38:39], s[82:83], 11
	v_lshl_or_b32 v2, s7, 3, v2
	s_add_u32 s38, s54, s38
	v_lshrrev_b32_e32 v3, 1, v2
	s_addc_u32 s39, s55, s39
	s_ashr_i32 s1, s0, 31
	v_xor_b32_e32 v3, v3, v18
	s_lshl_b64 s[50:51], s[0:1], 11
	v_readlane_b32 s1, v236, 9
	v_lshlrev_b32_e32 v2, 10, v2
	v_lshlrev_b32_e32 v3, 3, v3
	s_add_u32 s50, s1, s50
	v_readlane_b32 s1, v236, 11
	v_and_or_b32 v74, v3, 56, v2
	s_addc_u32 s51, s1, s51
	s_lshl_b32 s1, s7, 10
	v_lshlrev_b64 v[66:67], 1, v[74:75]
	s_add_i32 s1, s1, 0
	v_add_u32_e32 v2, 0x8000, v74
	v_bfe_u32 v93, v18, 5, 1
	v_lshrrev_b32_e32 v8, 1, v18
	v_mov_b32_e32 v3, v75
	v_lshl_add_u64 v[76:77], s[38:39], 0, v[66:67]
	s_add_i32 s86, s1, 0x8000
	v_bitop3_b32 v10, v93, v8, 7 bitop3:0x78
	v_lshl_add_u64 v[8:9], v[76:77], 0, s[8:9]
	s_mov_b32 m0, s86
	v_lshl_add_u64 v[78:79], s[50:51], 0, v[66:67]
	s_add_i32 s87, s1, 0xc000
	v_lshlrev_b64 v[68:69], 1, v[2:3]
	v_add_u32_e32 v4, 0x10000, v74
	s_waitcnt vmcnt(0) lgkmcnt(0)
	s_barrier
	v_mov_b32_e32 v5, v75
	global_load_lds_dwordx4 v[8:9], off
	v_lshl_add_u64 v[8:9], v[78:79], 0, s[8:9]
	s_mov_b32 m0, s87
	v_lshl_add_u64 v[80:81], s[38:39], 0, v[68:69]
	s_add_i32 s88, s1, 0x9000
	global_load_lds_dwordx4 v[8:9], off
	v_lshl_add_u64 v[2:3], v[80:81], 0, s[8:9]
	s_mov_b32 m0, s88
	v_lshl_add_u64 v[82:83], s[50:51], 0, v[68:69]
	s_add_i32 s89, s1, 0xd000
	v_lshlrev_b64 v[70:71], 1, v[4:5]
	v_add_u32_e32 v6, 0x18000, v74
	v_mov_b32_e32 v7, v75
	global_load_lds_dwordx4 v[2:3], off
	v_lshl_add_u64 v[2:3], v[82:83], 0, s[8:9]
	s_mov_b32 m0, s89
	v_lshl_add_u64 v[84:85], s[38:39], 0, v[70:71]
	s_add_i32 s91, s1, 0xa000
	global_load_lds_dwordx4 v[2:3], off
	v_lshl_add_u64 v[2:3], v[84:85], 0, s[8:9]
	s_mov_b32 m0, s91
	v_lshl_add_u64 v[86:87], s[50:51], 0, v[70:71]
	s_add_i32 s92, s1, 0xe000
	v_lshlrev_b64 v[72:73], 1, v[6:7]
	global_load_lds_dwordx4 v[2:3], off
	v_lshl_add_u64 v[2:3], v[86:87], 0, s[8:9]
	s_mov_b32 m0, s92
	v_lshl_add_u64 v[88:89], s[38:39], 0, v[72:73]
	s_add_i32 s93, s1, 0xb000
	v_and_b32_e32 v94, 31, v18
	global_load_lds_dwordx4 v[2:3], off
	v_lshl_add_u64 v[2:3], v[88:89], 0, s[8:9]
	s_mov_b32 m0, s93
	v_lshl_add_u64 v[90:91], s[50:51], 0, v[72:73]
	s_add_i32 s94, s1, 0xf000
	s_lshl_b32 s7, s4, 13
	v_lshlrev_b32_e32 v116, 7, v94
	global_load_lds_dwordx4 v[2:3], off
	v_lshl_add_u64 v[2:3], v[90:91], 0, s[8:9]
	s_mov_b32 m0, s94
	v_lshl_add_u32 v6, v10, 4, 0
	global_load_lds_dwordx4 v[2:3], off
	v_add3_u32 v74, v6, s7, v116
	ds_read_b128 v[2:5], v74 offset:16384
	s_lshl_b32 s38, s6, 13
	v_add3_u32 v96, v6, s38, v116
	v_bfe_u32 v117, v18, 1, 3
	ds_read_b128 v[6:9], v96
	ds_read_b128 v[10:13], v96 offset:4096
	ds_read_b128 v[14:17], v74 offset:20480
	v_bitop3_b32 v18, v93, v117, 2 bitop3:0x36
	v_lshl_add_u32 v18, v18, 4, 0
	v_add3_u32 v95, v18, s7, v116
	ds_read_b128 v[50:53], v95 offset:16384
	s_waitcnt lgkmcnt(0)
	v_mfma_f32_32x32x16_bf16 v[34:49], v[2:5], v[6:9], 0
	v_add3_u32 v97, v18, s38, v116
	ds_read_b128 v[98:101], v97
	ds_read_b128 v[102:105], v97 offset:4096
	ds_read_b128 v[106:109], v95 offset:20480
	s_mov_b32 m0, s1
	s_add_i32 s39, s1, 0x5000
	s_add_i32 s50, s1, 0x2000
	s_add_i32 s51, s1, 0x6000
	s_add_i32 s83, s1, 0x3000
	v_mfma_f32_32x32x16_bf16 v[18:33], v[2:5], v[10:13], 0
	s_add_i32 s90, s1, 0x7000
	s_add_i32 s33, s33, s95
	s_cmpk_lt_i32 s33, 0x1000
	s_cbranch_scc1 .Lg1_keep
	s_cmpk_ge_i32 s33, 0x1200
	s_cbranch_scc1 .Lg1_keep
	v_readlane_b32 s96, v236, 3
	s_lshr_b32 s97, s96, 3
	s_and_b32 s96, s96, 7
	s_lshl_b32 s98, s96, 5
	s_add_i32 s98, s98, s97
	s_add_i32 s98, s98, 0x1000
	s_add_i32 s99, s96, 0x1100
	s_cmp_lt_u32 s96, 4
	s_cselect_b32 s99, s99, 0x7fff
	s_cmp_eq_u32 s97, 32
	s_cselect_b32 s99, s99, 0x7fff
	s_cmp_lt_u32 s97, 32
	s_cselect_b32 s33, s98, s99
.Lg1_keep:
	s_waitcnt lgkmcnt(0)
	v_mfma_f32_32x32x16_bf16 v[34:49], v[50:53], v[98:101], v[34:49]
	v_mfma_f32_32x32x16_bf16 v[18:33], v[50:53], v[102:105], v[18:33]
	v_mfma_f32_32x32x16_bf16 v[50:65], v[14:17], v[6:9], 0
	v_mfma_f32_32x32x16_bf16 v[2:17], v[14:17], v[10:13], 0
	v_mfma_f32_32x32x16_bf16 v[50:65], v[106:109], v[98:101], v[50:65]
	v_bitop3_b32 v98, v93, v117, 4 bitop3:0x36
	v_lshl_add_u32 v99, v98, 4, 0
	v_add3_u32 v98, v99, s7, v116
	v_add3_u32 v99, v99, s38, v116
	v_mfma_f32_32x32x16_bf16 v[2:17], v[106:109], v[102:105], v[2:17]
	ds_read_b128 v[100:103], v98 offset:16384
	ds_read_b128 v[104:107], v99
	ds_read_b128 v[108:111], v99 offset:4096
	ds_read_b128 v[112:115], v98 offset:20480
	s_waitcnt lgkmcnt(0)
	v_mfma_f32_32x32x16_bf16 v[34:49], v[100:103], v[104:107], v[34:49]
	v_mfma_f32_32x32x16_bf16 v[18:33], v[100:103], v[108:111], v[18:33]
	v_bitop3_b32 v100, v93, v117, 6 bitop3:0x36
	v_lshl_add_u32 v101, v100, 4, 0
	v_add3_u32 v100, v101, s7, v116
	v_add3_u32 v101, v101, s38, v116
	s_add_i32 s7, s1, 0x4000
	s_add_i32 s38, s1, 0x1000
	s_cmpk_gt_i32 s33, 0x1103
	v_mfma_f32_32x32x16_bf16 v[50:65], v[112:115], v[104:107], v[50:65]
	v_mfma_f32_32x32x16_bf16 v[2:17], v[112:115], v[108:111], v[2:17]
	ds_read_b128 v[238:241], v100 offset:16384
	ds_read_b128 v[242:245], v101
	ds_read_b128 v[246:249], v101 offset:4096
	ds_read_b128 v[250:253], v100 offset:20480
	s_waitcnt vmcnt(0) lgkmcnt(0)
	s_barrier
; template <class Epi>
; DI void gemm_phase(const u16* __restrict__ A, const u16* __restrict__ B, int mtiles, int ntiles, char* lds, const Epi& epi) {
;     ...
;         for (int kt = 0; kt < 16; ++kt) {
;             if (kt + 1 < 16) GSTAGE((kt + 1) & 1, kt + 1, ga, gb);
;             const char* sa = lds + (kt & 1) * 32768; const char* sb = sa + 16384;
; #pragma unroll
;             for (int ks = 0; ks < 4; ++ks) {
;                 bf16x8 fw[2], fx[2];
; #pragma unroll
;                 for (int ct = 0; ct < 2; ++ct) fw[ct] = *(const bf16x8*)(sb + swz(wn * 64 + ct * 32 + r, 2 * ks + h));
; #pragma unroll
;                 for (int tt = 0; tt < 2; ++tt) fx[tt] = *(const bf16x8*)(sa + swz(wm * 64 + tt * 32 + r, 2 * ks + h));
; #pragma unroll
;                 for (int ct = 0; ct < 2; ++ct)
; #pragma unroll
;                     for (int tt = 0; tt < 2; ++tt) acc[ct][tt] = __builtin_amdgcn_mfma_f32_32x32x16_bf16(fw[ct], fx[tt], acc[ct][tt], 0, 0, 0);
;             }
	ds_read_b128 v[102:105], v74 offset:49152
	ds_read_b128 v[106:109], v96 offset:32768
	ds_read_b128 v[110:113], v96 offset:36864
	ds_read_b128 v[114:117], v74 offset:53248
	v_mfma_f32_32x32x16_bf16 v[34:49], v[238:241], v[242:245], v[34:49]
	v_mfma_f32_32x32x16_bf16 v[18:33], v[238:241], v[246:249], v[18:33]
	v_lshl_add_u64 v[254:255], v[76:77], 0, s[10:11]
	global_load_lds_dwordx4 v[254:255], off
	v_lshl_add_u64 v[254:255], v[78:79], 0, s[10:11]
	s_mov_b32 m0, s7
	s_nop 0
	global_load_lds_dwordx4 v[254:255], off
	v_mfma_f32_32x32x16_bf16 v[50:65], v[250:253], v[242:245], v[50:65]
	v_lshl_add_u64 v[254:255], v[80:81], 0, s[10:11]
	s_mov_b32 m0, s38
	s_nop 0
	global_load_lds_dwordx4 v[254:255], off
	v_mfma_f32_32x32x16_bf16 v[2:17], v[250:253], v[246:249], v[2:17]
	s_waitcnt lgkmcnt(0)
	ds_read_b128 v[238:241], v95 offset:49152
	ds_read_b128 v[242:245], v97 offset:32768
	ds_read_b128 v[246:249], v97 offset:36864
	ds_read_b128 v[250:253], v95 offset:53248
	v_mfma_f32_32x32x16_bf16 v[34:49], v[102:105], v[106:109], v[34:49]
	v_lshl_add_u64 v[254:255], v[82:83], 0, s[10:11]
	s_mov_b32 m0, s39
	s_nop 0
	global_load_lds_dwordx4 v[254:255], off
	v_mfma_f32_32x32x16_bf16 v[18:33], v[102:105], v[110:113], v[18:33]
	v_lshl_add_u64 v[254:255], v[84:85], 0, s[10:11]
	s_mov_b32 m0, s50
	s_nop 0
	global_load_lds_dwordx4 v[254:255], off
	v_mfma_f32_32x32x16_bf16 v[50:65], v[114:117], v[106:109], v[50:65]
	v_mfma_f32_32x32x16_bf16 v[2:17], v[114:117], v[110:113], v[2:17]
	s_waitcnt lgkmcnt(0)
	ds_read_b128 v[102:105], v98 offset:49152
	ds_read_b128 v[106:109], v99 offset:32768
	ds_read_b128 v[110:113], v99 offset:36864
	ds_read_b128 v[114:117], v98 offset:53248
	v_mfma_f32_32x32x16_bf16 v[34:49], v[238:241], v[242:245], v[34:49]
	v_lshl_add_u64 v[254:255], v[86:87], 0, s[10:11]
	s_mov_b32 m0, s51
	s_nop 0
	global_load_lds_dwordx4 v[254:255], off
	v_mfma_f32_32x32x16_bf16 v[18:33], v[238:241], v[246:249], v[18:33]
	v_lshl_add_u64 v[254:255], v[88:89], 0, s[10:11]
	s_mov_b32 m0, s83
	s_nop 0
	global_load_lds_dwordx4 v[254:255], off
	v_mfma_f32_32x32x16_bf16 v[50:65], v[250:253], v[242:245], v[50:65]
	v_mfma_f32_32x32x16_bf16 v[2:17], v[250:253], v[246:249], v[2:17]
	s_waitcnt lgkmcnt(0)
	ds_read_b128 v[238:241], v100 offset:49152
	ds_read_b128 v[242:245], v101 offset:32768
	ds_read_b128 v[246:249], v101 offset:36864
	ds_read_b128 v[250:253], v100 offset:53248
	v_mfma_f32_32x32x16_bf16 v[34:49], v[102:105], v[106:109], v[34:49]
	v_lshl_add_u64 v[254:255], v[90:91], 0, s[10:11]
	s_mov_b32 m0, s90
	s_nop 0
	global_load_lds_dwordx4 v[254:255], off
	v_mfma_f32_32x32x16_bf16 v[18:33], v[102:105], v[110:113], v[18:33]
	v_mfma_f32_32x32x16_bf16 v[50:65], v[114:117], v[106:109], v[50:65]
	v_mfma_f32_32x32x16_bf16 v[2:17], v[114:117], v[110:113], v[2:17]
	s_mov_b32 m0, s86
	s_waitcnt vmcnt(0) lgkmcnt(0)
	s_barrier
	ds_read_b128 v[102:105], v74 offset:16384
	ds_read_b128 v[106:109], v96
	ds_read_b128 v[110:113], v96 offset:4096
	ds_read_b128 v[114:117], v74 offset:20480
	v_mfma_f32_32x32x16_bf16 v[34:49], v[238:241], v[242:245], v[34:49]
	v_mfma_f32_32x32x16_bf16 v[18:33], v[238:241], v[246:249], v[18:33]
	v_lshl_add_u64 v[254:255], v[76:77], 0, s[12:13]
	global_load_lds_dwordx4 v[254:255], off
	v_lshl_add_u64 v[254:255], v[78:79], 0, s[12:13]
	s_mov_b32 m0, s87
	s_nop 0
	global_load_lds_dwordx4 v[254:255], off
	v_mfma_f32_32x32x16_bf16 v[50:65], v[250:253], v[242:245], v[50:65]
	v_lshl_add_u64 v[254:255], v[80:81], 0, s[12:13]
	s_mov_b32 m0, s88
	s_nop 0
	global_load_lds_dwordx4 v[254:255], off
	v_mfma_f32_32x32x16_bf16 v[2:17], v[250:253], v[246:249], v[2:17]
	s_waitcnt lgkmcnt(0)
	ds_read_b128 v[238:241], v95 offset:16384
	ds_read_b128 v[242:245], v97
	ds_read_b128 v[246:249], v97 offset:4096
	ds_read_b128 v[250:253], v95 offset:20480
	v_mfma_f32_32x32x16_bf16 v[34:49], v[102:105], v[106:109], v[34:49]
	v_lshl_add_u64 v[254:255], v[82:83], 0, s[12:13]
	s_mov_b32 m0, s89
	s_nop 0
	global_load_lds_dwordx4 v[254:255], off
	v_mfma_f32_32x32x16_bf16 v[18:33], v[102:105], v[110:113], v[18:33]
	v_lshl_add_u64 v[254:255], v[84:85], 0, s[12:13]
	s_mov_b32 m0, s91
	s_nop 0
	global_load_lds_dwordx4 v[254:255], off
	v_mfma_f32_32x32x16_bf16 v[50:65], v[114:117], v[106:109], v[50:65]
	v_mfma_f32_32x32x16_bf16 v[2:17], v[114:117], v[110:113], v[2:17]
	s_waitcnt lgkmcnt(0)
	ds_read_b128 v[102:105], v98 offset:16384
	ds_read_b128 v[106:109], v99
	ds_read_b128 v[110:113], v99 offset:4096
	ds_read_b128 v[114:117], v98 offset:20480
	v_mfma_f32_32x32x16_bf16 v[34:49], v[238:241], v[242:245], v[34:49]
	v_lshl_add_u64 v[254:255], v[86:87], 0, s[12:13]
	s_mov_b32 m0, s92
	s_nop 0
	global_load_lds_dwordx4 v[254:255], off
	v_mfma_f32_32x32x16_bf16 v[18:33], v[238:241], v[246:249], v[18:33]
	v_lshl_add_u64 v[254:255], v[88:89], 0, s[12:13]
	s_mov_b32 m0, s93
	s_nop 0
	global_load_lds_dwordx4 v[254:255], off
	v_mfma_f32_32x32x16_bf16 v[50:65], v[250:253], v[242:245], v[50:65]
	v_mfma_f32_32x32x16_bf16 v[2:17], v[250:253], v[246:249], v[2:17]
	s_waitcnt lgkmcnt(0)
	ds_read_b128 v[238:241], v100 offset:16384
	ds_read_b128 v[242:245], v101
	ds_read_b128 v[246:249], v101 offset:4096
	ds_read_b128 v[250:253], v100 offset:20480
	v_mfma_f32_32x32x16_bf16 v[34:49], v[102:105], v[106:109], v[34:49]
	v_lshl_add_u64 v[254:255], v[90:91], 0, s[12:13]
	s_mov_b32 m0, s94
	s_nop 0
	global_load_lds_dwordx4 v[254:255], off
	v_mfma_f32_32x32x16_bf16 v[18:33], v[102:105], v[110:113], v[18:33]
	v_mfma_f32_32x32x16_bf16 v[50:65], v[114:117], v[106:109], v[50:65]
	v_mfma_f32_32x32x16_bf16 v[2:17], v[114:117], v[110:113], v[2:17]
	s_mov_b32 m0, s1
	s_waitcnt vmcnt(0) lgkmcnt(0)
	s_barrier
; template <class Epi>
; DI void gemm_phase(const u16* __restrict__ A, const u16* __restrict__ B, int mtiles, int ntiles, char* lds, const Epi& epi) {
;     ...
;         for (int kt = 0; kt < 16; ++kt) {
;             if (kt + 1 < 16) GSTAGE((kt + 1) & 1, kt + 1, ga, gb);
;             const char* sa = lds + (kt & 1) * 32768; const char* sb = sa + 16384;
; #pragma unroll
;             for (int ks = 0; ks < 4; ++ks) {
;                 bf16x8 fw[2], fx[2];
; #pragma unroll
;                 for (int ct = 0; ct < 2; ++ct) fw[ct] = *(const bf16x8*)(sb + swz(wn * 64 + ct * 32 + r, 2 * ks + h));
; #pragma unroll
;                 for (int tt = 0; tt < 2; ++tt) fx[tt] = *(const bf16x8*)(sa + swz(wm * 64 + tt * 32 + r, 2 * ks + h));
; #pragma unroll
;                 for (int ct = 0; ct < 2; ++ct)
; #pragma unroll
;                     for (int tt = 0; tt < 2; ++tt) acc[ct][tt] = __builtin_amdgcn_mfma_f32_32x32x16_bf16(fw[ct], fx[tt], acc[ct][tt], 0, 0, 0);
;             }
	ds_read_b128 v[102:105], v74 offset:49152
	ds_read_b128 v[106:109], v96 offset:32768
	ds_read_b128 v[110:113], v96 offset:36864
	ds_read_b128 v[114:117], v74 offset:53248
	v_mfma_f32_32x32x16_bf16 v[34:49], v[238:241], v[242:245], v[34:49]
	v_mfma_f32_32x32x16_bf16 v[18:33], v[238:241], v[246:249], v[18:33]
	v_lshl_add_u64 v[254:255], v[76:77], 0, s[14:15]
	global_load_lds_dwordx4 v[254:255], off
	v_lshl_add_u64 v[254:255], v[78:79], 0, s[14:15]
	s_mov_b32 m0, s7
	s_nop 0
	global_load_lds_dwordx4 v[254:255], off
	v_mfma_f32_32x32x16_bf16 v[50:65], v[250:253], v[242:245], v[50:65]
	v_lshl_add_u64 v[254:255], v[80:81], 0, s[14:15]
	s_mov_b32 m0, s38
	s_nop 0
	global_load_lds_dwordx4 v[254:255], off
	v_mfma_f32_32x32x16_bf16 v[2:17], v[250:253], v[246:249], v[2:17]
	s_waitcnt lgkmcnt(0)
	ds_read_b128 v[238:241], v95 offset:49152
	ds_read_b128 v[242:245], v97 offset:32768
	ds_read_b128 v[246:249], v97 offset:36864
	ds_read_b128 v[250:253], v95 offset:53248
	v_mfma_f32_32x32x16_bf16 v[34:49], v[102:105], v[106:109], v[34:49]
	v_lshl_add_u64 v[254:255], v[82:83], 0, s[14:15]
	s_mov_b32 m0, s39
	s_nop 0
	global_load_lds_dwordx4 v[254:255], off
	v_mfma_f32_32x32x16_bf16 v[18:33], v[102:105], v[110:113], v[18:33]
	v_lshl_add_u64 v[254:255], v[84:85], 0, s[14:15]
	s_mov_b32 m0, s50
	s_nop 0
	global_load_lds_dwordx4 v[254:255], off
	v_mfma_f32_32x32x16_bf16 v[50:65], v[114:117], v[106:109], v[50:65]
	v_mfma_f32_32x32x16_bf16 v[2:17], v[114:117], v[110:113], v[2:17]
	s_waitcnt lgkmcnt(0)
	ds_read_b128 v[102:105], v98 offset:49152
	ds_read_b128 v[106:109], v99 offset:32768
	ds_read_b128 v[110:113], v99 offset:36864
	ds_read_b128 v[114:117], v98 offset:53248
	v_mfma_f32_32x32x16_bf16 v[34:49], v[238:241], v[242:245], v[34:49]
	v_lshl_add_u64 v[254:255], v[86:87], 0, s[14:15]
	s_mov_b32 m0, s51
	s_nop 0
	global_load_lds_dwordx4 v[254:255], off
	v_mfma_f32_32x32x16_bf16 v[18:33], v[238:241], v[246:249], v[18:33]
	v_lshl_add_u64 v[254:255], v[88:89], 0, s[14:15]
	s_mov_b32 m0, s83
	s_nop 0
	global_load_lds_dwordx4 v[254:255], off
	v_mfma_f32_32x32x16_bf16 v[50:65], v[250:253], v[242:245], v[50:65]
	v_mfma_f32_32x32x16_bf16 v[2:17], v[250:253], v[246:249], v[2:17]
	s_waitcnt lgkmcnt(0)
	ds_read_b128 v[238:241], v100 offset:49152
	ds_read_b128 v[242:245], v101 offset:32768
	ds_read_b128 v[246:249], v101 offset:36864
	ds_read_b128 v[250:253], v100 offset:53248
	v_mfma_f32_32x32x16_bf16 v[34:49], v[102:105], v[106:109], v[34:49]
	v_lshl_add_u64 v[254:255], v[90:91], 0, s[14:15]
	s_mov_b32 m0, s90
	s_nop 0
	global_load_lds_dwordx4 v[254:255], off
	v_mfma_f32_32x32x16_bf16 v[18:33], v[102:105], v[110:113], v[18:33]
	v_mfma_f32_32x32x16_bf16 v[50:65], v[114:117], v[106:109], v[50:65]
	v_mfma_f32_32x32x16_bf16 v[2:17], v[114:117], v[110:113], v[2:17]
	s_mov_b32 m0, s86
	s_waitcnt vmcnt(0) lgkmcnt(0)
	s_barrier
	ds_read_b128 v[102:105], v74 offset:16384
	ds_read_b128 v[106:109], v96
	ds_read_b128 v[110:113], v96 offset:4096
	ds_read_b128 v[114:117], v74 offset:20480
	v_mfma_f32_32x32x16_bf16 v[34:49], v[238:241], v[242:245], v[34:49]
	v_mfma_f32_32x32x16_bf16 v[18:33], v[238:241], v[246:249], v[18:33]
	v_lshl_add_u64 v[254:255], v[76:77], 0, s[16:17]
	global_load_lds_dwordx4 v[254:255], off
	v_lshl_add_u64 v[254:255], v[78:79], 0, s[16:17]
	s_mov_b32 m0, s87
	s_nop 0
	global_load_lds_dwordx4 v[254:255], off
	v_mfma_f32_32x32x16_bf16 v[50:65], v[250:253], v[242:245], v[50:65]
	v_lshl_add_u64 v[254:255], v[80:81], 0, s[16:17]
	s_mov_b32 m0, s88
	s_nop 0
	global_load_lds_dwordx4 v[254:255], off
	v_mfma_f32_32x32x16_bf16 v[2:17], v[250:253], v[246:249], v[2:17]
	s_waitcnt lgkmcnt(0)
	ds_read_b128 v[238:241], v95 offset:16384
	ds_read_b128 v[242:245], v97
	ds_read_b128 v[246:249], v97 offset:4096
	ds_read_b128 v[250:253], v95 offset:20480
	v_mfma_f32_32x32x16_bf16 v[34:49], v[102:105], v[106:109], v[34:49]
	v_lshl_add_u64 v[254:255], v[82:83], 0, s[16:17]
	s_mov_b32 m0, s89
	s_nop 0
	global_load_lds_dwordx4 v[254:255], off
	v_mfma_f32_32x32x16_bf16 v[18:33], v[102:105], v[110:113], v[18:33]
	v_lshl_add_u64 v[254:255], v[84:85], 0, s[16:17]
	s_mov_b32 m0, s91
	s_nop 0
	global_load_lds_dwordx4 v[254:255], off
	v_mfma_f32_32x32x16_bf16 v[50:65], v[114:117], v[106:109], v[50:65]
	v_mfma_f32_32x32x16_bf16 v[2:17], v[114:117], v[110:113], v[2:17]
	s_waitcnt lgkmcnt(0)
	ds_read_b128 v[102:105], v98 offset:16384
	ds_read_b128 v[106:109], v99
	ds_read_b128 v[110:113], v99 offset:4096
	ds_read_b128 v[114:117], v98 offset:20480
	v_mfma_f32_32x32x16_bf16 v[34:49], v[238:241], v[242:245], v[34:49]
	v_lshl_add_u64 v[254:255], v[86:87], 0, s[16:17]
	s_mov_b32 m0, s92
	s_nop 0
	global_load_lds_dwordx4 v[254:255], off
	v_mfma_f32_32x32x16_bf16 v[18:33], v[238:241], v[246:249], v[18:33]
	v_lshl_add_u64 v[254:255], v[88:89], 0, s[16:17]
	s_mov_b32 m0, s93
	s_nop 0
	global_load_lds_dwordx4 v[254:255], off
	v_mfma_f32_32x32x16_bf16 v[50:65], v[250:253], v[242:245], v[50:65]
	v_mfma_f32_32x32x16_bf16 v[2:17], v[250:253], v[246:249], v[2:17]
	s_waitcnt lgkmcnt(0)
	ds_read_b128 v[238:241], v100 offset:16384
	ds_read_b128 v[242:245], v101
	ds_read_b128 v[246:249], v101 offset:4096
	ds_read_b128 v[250:253], v100 offset:20480
	v_mfma_f32_32x32x16_bf16 v[34:49], v[102:105], v[106:109], v[34:49]
	v_lshl_add_u64 v[254:255], v[90:91], 0, s[16:17]
	s_mov_b32 m0, s94
	s_nop 0
	global_load_lds_dwordx4 v[254:255], off
	v_mfma_f32_32x32x16_bf16 v[18:33], v[102:105], v[110:113], v[18:33]
	v_mfma_f32_32x32x16_bf16 v[50:65], v[114:117], v[106:109], v[50:65]
	v_mfma_f32_32x32x16_bf16 v[2:17], v[114:117], v[110:113], v[2:17]
	s_mov_b32 m0, s1
	s_waitcnt vmcnt(0) lgkmcnt(0)
	s_barrier
; template <class Epi>
; DI void gemm_phase(const u16* __restrict__ A, const u16* __restrict__ B, int mtiles, int ntiles, char* lds, const Epi& epi) {
;     ...
;         for (int kt = 0; kt < 16; ++kt) {
;             if (kt + 1 < 16) GSTAGE((kt + 1) & 1, kt + 1, ga, gb);
;             const char* sa = lds + (kt & 1) * 32768; const char* sb = sa + 16384;
; #pragma unroll
;             for (int ks = 0; ks < 4; ++ks) {
;                 bf16x8 fw[2], fx[2];
; #pragma unroll
;                 for (int ct = 0; ct < 2; ++ct) fw[ct] = *(const bf16x8*)(sb + swz(wn * 64 + ct * 32 + r, 2 * ks + h));
; #pragma unroll
;                 for (int tt = 0; tt < 2; ++tt) fx[tt] = *(const bf16x8*)(sa + swz(wm * 64 + tt * 32 + r, 2 * ks + h));
; #pragma unroll
;                 for (int ct = 0; ct < 2; ++ct)
; #pragma unroll
;                     for (int tt = 0; tt < 2; ++tt) acc[ct][tt] = __builtin_amdgcn_mfma_f32_32x32x16_bf16(fw[ct], fx[tt], acc[ct][tt], 0, 0, 0);
;             }
	ds_read_b128 v[102:105], v74 offset:49152
	ds_read_b128 v[106:109], v96 offset:32768
	ds_read_b128 v[110:113], v96 offset:36864
	ds_read_b128 v[114:117], v74 offset:53248
	v_mfma_f32_32x32x16_bf16 v[34:49], v[238:241], v[242:245], v[34:49]
	v_mfma_f32_32x32x16_bf16 v[18:33], v[238:241], v[246:249], v[18:33]
	v_lshl_add_u64 v[254:255], v[76:77], 0, s[18:19]
	global_load_lds_dwordx4 v[254:255], off
	v_lshl_add_u64 v[254:255], v[78:79], 0, s[18:19]
	s_mov_b32 m0, s7
	s_nop 0
	global_load_lds_dwordx4 v[254:255], off
	v_mfma_f32_32x32x16_bf16 v[50:65], v[250:253], v[242:245], v[50:65]
	v_lshl_add_u64 v[254:255], v[80:81], 0, s[18:19]
	s_mov_b32 m0, s38
	s_nop 0
	global_load_lds_dwordx4 v[254:255], off
	v_mfma_f32_32x32x16_bf16 v[2:17], v[250:253], v[246:249], v[2:17]
	s_waitcnt lgkmcnt(0)
	ds_read_b128 v[238:241], v95 offset:49152
	ds_read_b128 v[242:245], v97 offset:32768
	ds_read_b128 v[246:249], v97 offset:36864
	ds_read_b128 v[250:253], v95 offset:53248
	v_mfma_f32_32x32x16_bf16 v[34:49], v[102:105], v[106:109], v[34:49]
	v_lshl_add_u64 v[254:255], v[82:83], 0, s[18:19]
	s_mov_b32 m0, s39
	s_nop 0
	global_load_lds_dwordx4 v[254:255], off
	v_mfma_f32_32x32x16_bf16 v[18:33], v[102:105], v[110:113], v[18:33]
	v_lshl_add_u64 v[254:255], v[84:85], 0, s[18:19]
	s_mov_b32 m0, s50
	s_nop 0
	global_load_lds_dwordx4 v[254:255], off
	v_mfma_f32_32x32x16_bf16 v[50:65], v[114:117], v[106:109], v[50:65]
	v_mfma_f32_32x32x16_bf16 v[2:17], v[114:117], v[110:113], v[2:17]
	s_waitcnt lgkmcnt(0)
	ds_read_b128 v[102:105], v98 offset:49152
	ds_read_b128 v[106:109], v99 offset:32768
	ds_read_b128 v[110:113], v99 offset:36864
	ds_read_b128 v[114:117], v98 offset:53248
	v_mfma_f32_32x32x16_bf16 v[34:49], v[238:241], v[242:245], v[34:49]
	v_lshl_add_u64 v[254:255], v[86:87], 0, s[18:19]
	s_mov_b32 m0, s51
	s_nop 0
	global_load_lds_dwordx4 v[254:255], off
	v_mfma_f32_32x32x16_bf16 v[18:33], v[238:241], v[246:249], v[18:33]
	v_lshl_add_u64 v[254:255], v[88:89], 0, s[18:19]
	s_mov_b32 m0, s83
	s_nop 0
	global_load_lds_dwordx4 v[254:255], off
	v_mfma_f32_32x32x16_bf16 v[50:65], v[250:253], v[242:245], v[50:65]
	v_mfma_f32_32x32x16_bf16 v[2:17], v[250:253], v[246:249], v[2:17]
	s_waitcnt lgkmcnt(0)
	ds_read_b128 v[238:241], v100 offset:49152
	ds_read_b128 v[242:245], v101 offset:32768
	ds_read_b128 v[246:249], v101 offset:36864
	ds_read_b128 v[250:253], v100 offset:53248
	v_mfma_f32_32x32x16_bf16 v[34:49], v[102:105], v[106:109], v[34:49]
	v_lshl_add_u64 v[254:255], v[90:91], 0, s[18:19]
	s_mov_b32 m0, s90
	s_nop 0
	global_load_lds_dwordx4 v[254:255], off
	v_mfma_f32_32x32x16_bf16 v[18:33], v[102:105], v[110:113], v[18:33]
	v_mfma_f32_32x32x16_bf16 v[50:65], v[114:117], v[106:109], v[50:65]
	v_mfma_f32_32x32x16_bf16 v[2:17], v[114:117], v[110:113], v[2:17]
	s_mov_b32 m0, s86
	s_waitcnt vmcnt(0) lgkmcnt(0)
	s_barrier
	ds_read_b128 v[102:105], v74 offset:16384
	ds_read_b128 v[106:109], v96
	ds_read_b128 v[110:113], v96 offset:4096
	ds_read_b128 v[114:117], v74 offset:20480
	v_mfma_f32_32x32x16_bf16 v[34:49], v[238:241], v[242:245], v[34:49]
	v_mfma_f32_32x32x16_bf16 v[18:33], v[238:241], v[246:249], v[18:33]
	v_lshl_add_u64 v[254:255], v[76:77], 0, s[20:21]
	global_load_lds_dwordx4 v[254:255], off
	v_lshl_add_u64 v[254:255], v[78:79], 0, s[20:21]
	s_mov_b32 m0, s87
	s_nop 0
	global_load_lds_dwordx4 v[254:255], off
	v_mfma_f32_32x32x16_bf16 v[50:65], v[250:253], v[242:245], v[50:65]
	v_lshl_add_u64 v[254:255], v[80:81], 0, s[20:21]
	s_mov_b32 m0, s88
	s_nop 0
	global_load_lds_dwordx4 v[254:255], off
	v_mfma_f32_32x32x16_bf16 v[2:17], v[250:253], v[246:249], v[2:17]
	s_waitcnt lgkmcnt(0)
	ds_read_b128 v[238:241], v95 offset:16384
	ds_read_b128 v[242:245], v97
	ds_read_b128 v[246:249], v97 offset:4096
	ds_read_b128 v[250:253], v95 offset:20480
	v_mfma_f32_32x32x16_bf16 v[34:49], v[102:105], v[106:109], v[34:49]
	v_lshl_add_u64 v[254:255], v[82:83], 0, s[20:21]
	s_mov_b32 m0, s89
	s_nop 0
	global_load_lds_dwordx4 v[254:255], off
	v_mfma_f32_32x32x16_bf16 v[18:33], v[102:105], v[110:113], v[18:33]
	v_lshl_add_u64 v[254:255], v[84:85], 0, s[20:21]
	s_mov_b32 m0, s91
	s_nop 0
	global_load_lds_dwordx4 v[254:255], off
	v_mfma_f32_32x32x16_bf16 v[50:65], v[114:117], v[106:109], v[50:65]
	v_mfma_f32_32x32x16_bf16 v[2:17], v[114:117], v[110:113], v[2:17]
	s_waitcnt lgkmcnt(0)
	ds_read_b128 v[102:105], v98 offset:16384
	ds_read_b128 v[106:109], v99
	ds_read_b128 v[110:113], v99 offset:4096
	ds_read_b128 v[114:117], v98 offset:20480
	v_mfma_f32_32x32x16_bf16 v[34:49], v[238:241], v[242:245], v[34:49]
	v_lshl_add_u64 v[254:255], v[86:87], 0, s[20:21]
	s_mov_b32 m0, s92
	s_nop 0
	global_load_lds_dwordx4 v[254:255], off
	v_mfma_f32_32x32x16_bf16 v[18:33], v[238:241], v[246:249], v[18:33]
	v_lshl_add_u64 v[254:255], v[88:89], 0, s[20:21]
	s_mov_b32 m0, s93
	s_nop 0
	global_load_lds_dwordx4 v[254:255], off
	v_mfma_f32_32x32x16_bf16 v[50:65], v[250:253], v[242:245], v[50:65]
	v_mfma_f32_32x32x16_bf16 v[2:17], v[250:253], v[246:249], v[2:17]
	s_waitcnt lgkmcnt(0)
	ds_read_b128 v[238:241], v100 offset:16384
	ds_read_b128 v[242:245], v101
	ds_read_b128 v[246:249], v101 offset:4096
	ds_read_b128 v[250:253], v100 offset:20480
	v_mfma_f32_32x32x16_bf16 v[34:49], v[102:105], v[106:109], v[34:49]
	v_lshl_add_u64 v[254:255], v[90:91], 0, s[20:21]
	s_mov_b32 m0, s94
	s_nop 0
	global_load_lds_dwordx4 v[254:255], off
	v_mfma_f32_32x32x16_bf16 v[18:33], v[102:105], v[110:113], v[18:33]
	v_mfma_f32_32x32x16_bf16 v[50:65], v[114:117], v[106:109], v[50:65]
	v_mfma_f32_32x32x16_bf16 v[2:17], v[114:117], v[110:113], v[2:17]
	s_mov_b32 m0, s1
	s_waitcnt vmcnt(0) lgkmcnt(0)
	s_barrier
; template <class Epi>
; DI void gemm_phase(const u16* __restrict__ A, const u16* __restrict__ B, int mtiles, int ntiles, char* lds, const Epi& epi) {
;     ...
;         for (int kt = 0; kt < 16; ++kt) {
;             if (kt + 1 < 16) GSTAGE((kt + 1) & 1, kt + 1, ga, gb);
;             const char* sa = lds + (kt & 1) * 32768; const char* sb = sa + 16384;
; #pragma unroll
;             for (int ks = 0; ks < 4; ++ks) {
;                 bf16x8 fw[2], fx[2];
; #pragma unroll
;                 for (int ct = 0; ct < 2; ++ct) fw[ct] = *(const bf16x8*)(sb + swz(wn * 64 + ct * 32 + r, 2 * ks + h));
; #pragma unroll
;                 for (int tt = 0; tt < 2; ++tt) fx[tt] = *(const bf16x8*)(sa + swz(wm * 64 + tt * 32 + r, 2 * ks + h));
; #pragma unroll
;                 for (int ct = 0; ct < 2; ++ct)
; #pragma unroll
;                     for (int tt = 0; tt < 2; ++tt) acc[ct][tt] = __builtin_amdgcn_mfma_f32_32x32x16_bf16(fw[ct], fx[tt], acc[ct][tt], 0, 0, 0);
;             }
	ds_read_b128 v[102:105], v74 offset:49152
	ds_read_b128 v[106:109], v96 offset:32768
	ds_read_b128 v[110:113], v96 offset:36864
	ds_read_b128 v[114:117], v74 offset:53248
	v_mfma_f32_32x32x16_bf16 v[34:49], v[238:241], v[242:245], v[34:49]
	v_mfma_f32_32x32x16_bf16 v[18:33], v[238:241], v[246:249], v[18:33]
	v_lshl_add_u64 v[254:255], v[76:77], 0, s[22:23]
	global_load_lds_dwordx4 v[254:255], off
	v_lshl_add_u64 v[254:255], v[78:79], 0, s[22:23]
	s_mov_b32 m0, s7
	s_nop 0
	global_load_lds_dwordx4 v[254:255], off
	v_mfma_f32_32x32x16_bf16 v[50:65], v[250:253], v[242:245], v[50:65]
	v_lshl_add_u64 v[254:255], v[80:81], 0, s[22:23]
	s_mov_b32 m0, s38
	s_nop 0
	global_load_lds_dwordx4 v[254:255], off
	v_mfma_f32_32x32x16_bf16 v[2:17], v[250:253], v[246:249], v[2:17]
	s_waitcnt lgkmcnt(0)
	ds_read_b128 v[238:241], v95 offset:49152
	ds_read_b128 v[242:245], v97 offset:32768
	ds_read_b128 v[246:249], v97 offset:36864
	ds_read_b128 v[250:253], v95 offset:53248
	v_mfma_f32_32x32x16_bf16 v[34:49], v[102:105], v[106:109], v[34:49]
	v_lshl_add_u64 v[254:255], v[82:83], 0, s[22:23]
	s_mov_b32 m0, s39
	s_nop 0
	global_load_lds_dwordx4 v[254:255], off
	v_mfma_f32_32x32x16_bf16 v[18:33], v[102:105], v[110:113], v[18:33]
	v_lshl_add_u64 v[254:255], v[84:85], 0, s[22:23]
	s_mov_b32 m0, s50
	s_nop 0
	global_load_lds_dwordx4 v[254:255], off
	v_mfma_f32_32x32x16_bf16 v[50:65], v[114:117], v[106:109], v[50:65]
	v_mfma_f32_32x32x16_bf16 v[2:17], v[114:117], v[110:113], v[2:17]
	s_waitcnt lgkmcnt(0)
	ds_read_b128 v[102:105], v98 offset:49152
	ds_read_b128 v[106:109], v99 offset:32768
	ds_read_b128 v[110:113], v99 offset:36864
	ds_read_b128 v[114:117], v98 offset:53248
	v_mfma_f32_32x32x16_bf16 v[34:49], v[238:241], v[242:245], v[34:49]
	v_lshl_add_u64 v[254:255], v[86:87], 0, s[22:23]
	s_mov_b32 m0, s51
	s_nop 0
	global_load_lds_dwordx4 v[254:255], off
	v_mfma_f32_32x32x16_bf16 v[18:33], v[238:241], v[246:249], v[18:33]
	v_lshl_add_u64 v[254:255], v[88:89], 0, s[22:23]
	s_mov_b32 m0, s83
	s_nop 0
	global_load_lds_dwordx4 v[254:255], off
	v_mfma_f32_32x32x16_bf16 v[50:65], v[250:253], v[242:245], v[50:65]
	v_mfma_f32_32x32x16_bf16 v[2:17], v[250:253], v[246:249], v[2:17]
	s_waitcnt lgkmcnt(0)
	ds_read_b128 v[238:241], v100 offset:49152
	ds_read_b128 v[242:245], v101 offset:32768
	ds_read_b128 v[246:249], v101 offset:36864
	ds_read_b128 v[250:253], v100 offset:53248
	v_mfma_f32_32x32x16_bf16 v[34:49], v[102:105], v[106:109], v[34:49]
	v_lshl_add_u64 v[254:255], v[90:91], 0, s[22:23]
	s_mov_b32 m0, s90
	s_nop 0
	global_load_lds_dwordx4 v[254:255], off
	v_mfma_f32_32x32x16_bf16 v[18:33], v[102:105], v[110:113], v[18:33]
	v_mfma_f32_32x32x16_bf16 v[50:65], v[114:117], v[106:109], v[50:65]
	v_mfma_f32_32x32x16_bf16 v[2:17], v[114:117], v[110:113], v[2:17]
	s_mov_b32 m0, s86
	s_waitcnt vmcnt(0) lgkmcnt(0)
	s_barrier
	ds_read_b128 v[102:105], v74 offset:16384
	ds_read_b128 v[106:109], v96
	ds_read_b128 v[110:113], v96 offset:4096
	ds_read_b128 v[114:117], v74 offset:20480
	v_mfma_f32_32x32x16_bf16 v[34:49], v[238:241], v[242:245], v[34:49]
	v_mfma_f32_32x32x16_bf16 v[18:33], v[238:241], v[246:249], v[18:33]
	v_lshl_add_u64 v[254:255], v[76:77], 0, s[24:25]
	global_load_lds_dwordx4 v[254:255], off
	v_lshl_add_u64 v[254:255], v[78:79], 0, s[24:25]
	s_mov_b32 m0, s87
	s_nop 0
	global_load_lds_dwordx4 v[254:255], off
	v_mfma_f32_32x32x16_bf16 v[50:65], v[250:253], v[242:245], v[50:65]
	v_lshl_add_u64 v[254:255], v[80:81], 0, s[24:25]
	s_mov_b32 m0, s88
	s_nop 0
	global_load_lds_dwordx4 v[254:255], off
	v_mfma_f32_32x32x16_bf16 v[2:17], v[250:253], v[246:249], v[2:17]
	s_waitcnt lgkmcnt(0)
	ds_read_b128 v[238:241], v95 offset:16384
	ds_read_b128 v[242:245], v97
	ds_read_b128 v[246:249], v97 offset:4096
	ds_read_b128 v[250:253], v95 offset:20480
	v_mfma_f32_32x32x16_bf16 v[34:49], v[102:105], v[106:109], v[34:49]
	v_lshl_add_u64 v[254:255], v[82:83], 0, s[24:25]
	s_mov_b32 m0, s89
	s_nop 0
	global_load_lds_dwordx4 v[254:255], off
	v_mfma_f32_32x32x16_bf16 v[18:33], v[102:105], v[110:113], v[18:33]
	v_lshl_add_u64 v[254:255], v[84:85], 0, s[24:25]
	s_mov_b32 m0, s91
	s_nop 0
	global_load_lds_dwordx4 v[254:255], off
	v_mfma_f32_32x32x16_bf16 v[50:65], v[114:117], v[106:109], v[50:65]
	v_mfma_f32_32x32x16_bf16 v[2:17], v[114:117], v[110:113], v[2:17]
	s_waitcnt lgkmcnt(0)
	ds_read_b128 v[102:105], v98 offset:16384
	ds_read_b128 v[106:109], v99
	ds_read_b128 v[110:113], v99 offset:4096
	ds_read_b128 v[114:117], v98 offset:20480
	v_mfma_f32_32x32x16_bf16 v[34:49], v[238:241], v[242:245], v[34:49]
	v_lshl_add_u64 v[254:255], v[86:87], 0, s[24:25]
	s_mov_b32 m0, s92
	s_nop 0
	global_load_lds_dwordx4 v[254:255], off
	v_mfma_f32_32x32x16_bf16 v[18:33], v[238:241], v[246:249], v[18:33]
	v_lshl_add_u64 v[254:255], v[88:89], 0, s[24:25]
	s_mov_b32 m0, s93
	s_nop 0
	global_load_lds_dwordx4 v[254:255], off
	v_mfma_f32_32x32x16_bf16 v[50:65], v[250:253], v[242:245], v[50:65]
	v_mfma_f32_32x32x16_bf16 v[2:17], v[250:253], v[246:249], v[2:17]
	s_waitcnt lgkmcnt(0)
	ds_read_b128 v[238:241], v100 offset:16384
	ds_read_b128 v[242:245], v101
	ds_read_b128 v[246:249], v101 offset:4096
	ds_read_b128 v[250:253], v100 offset:20480
	v_mfma_f32_32x32x16_bf16 v[34:49], v[102:105], v[106:109], v[34:49]
	v_lshl_add_u64 v[254:255], v[90:91], 0, s[24:25]
	s_mov_b32 m0, s94
	s_nop 0
	global_load_lds_dwordx4 v[254:255], off
	v_mfma_f32_32x32x16_bf16 v[18:33], v[102:105], v[110:113], v[18:33]
	v_mfma_f32_32x32x16_bf16 v[50:65], v[114:117], v[106:109], v[50:65]
	v_mfma_f32_32x32x16_bf16 v[2:17], v[114:117], v[110:113], v[2:17]
	s_mov_b32 m0, s1
	s_waitcnt vmcnt(0) lgkmcnt(0)
	s_barrier
; template <class Epi>
; DI void gemm_phase(const u16* __restrict__ A, const u16* __restrict__ B, int mtiles, int ntiles, char* lds, const Epi& epi) {
;     ...
;         for (int kt = 0; kt < 16; ++kt) {
;             if (kt + 1 < 16) GSTAGE((kt + 1) & 1, kt + 1, ga, gb);
;             const char* sa = lds + (kt & 1) * 32768; const char* sb = sa + 16384;
; #pragma unroll
;             for (int ks = 0; ks < 4; ++ks) {
;                 bf16x8 fw[2], fx[2];
; #pragma unroll
;                 for (int ct = 0; ct < 2; ++ct) fw[ct] = *(const bf16x8*)(sb + swz(wn * 64 + ct * 32 + r, 2 * ks + h));
; #pragma unroll
;                 for (int tt = 0; tt < 2; ++tt) fx[tt] = *(const bf16x8*)(sa + swz(wm * 64 + tt * 32 + r, 2 * ks + h));
; #pragma unroll
;                 for (int ct = 0; ct < 2; ++ct)
; #pragma unroll
;                     for (int tt = 0; tt < 2; ++tt) acc[ct][tt] = __builtin_amdgcn_mfma_f32_32x32x16_bf16(fw[ct], fx[tt], acc[ct][tt], 0, 0, 0);
;             }
	ds_read_b128 v[102:105], v74 offset:49152
	ds_read_b128 v[106:109], v96 offset:32768
	ds_read_b128 v[110:113], v96 offset:36864
	ds_read_b128 v[114:117], v74 offset:53248
	v_mfma_f32_32x32x16_bf16 v[34:49], v[238:241], v[242:245], v[34:49]
	v_mfma_f32_32x32x16_bf16 v[18:33], v[238:241], v[246:249], v[18:33]
	v_lshl_add_u64 v[254:255], v[76:77], 0, s[26:27]
	global_load_lds_dwordx4 v[254:255], off
	v_lshl_add_u64 v[254:255], v[78:79], 0, s[26:27]
	s_mov_b32 m0, s7
	s_nop 0
	global_load_lds_dwordx4 v[254:255], off
	v_mfma_f32_32x32x16_bf16 v[50:65], v[250:253], v[242:245], v[50:65]
	v_lshl_add_u64 v[254:255], v[80:81], 0, s[26:27]
	s_mov_b32 m0, s38
	s_nop 0
	global_load_lds_dwordx4 v[254:255], off
	v_mfma_f32_32x32x16_bf16 v[2:17], v[250:253], v[246:249], v[2:17]
	s_waitcnt lgkmcnt(0)
	ds_read_b128 v[238:241], v95 offset:49152
	ds_read_b128 v[242:245], v97 offset:32768
	ds_read_b128 v[246:249], v97 offset:36864
	ds_read_b128 v[250:253], v95 offset:53248
	v_mfma_f32_32x32x16_bf16 v[34:49], v[102:105], v[106:109], v[34:49]
	v_lshl_add_u64 v[254:255], v[82:83], 0, s[26:27]
	s_mov_b32 m0, s39
	s_nop 0
	global_load_lds_dwordx4 v[254:255], off
	v_mfma_f32_32x32x16_bf16 v[18:33], v[102:105], v[110:113], v[18:33]
	v_lshl_add_u64 v[254:255], v[84:85], 0, s[26:27]
	s_mov_b32 m0, s50
	s_nop 0
	global_load_lds_dwordx4 v[254:255], off
	v_mfma_f32_32x32x16_bf16 v[50:65], v[114:117], v[106:109], v[50:65]
	v_mfma_f32_32x32x16_bf16 v[2:17], v[114:117], v[110:113], v[2:17]
	s_waitcnt lgkmcnt(0)
	ds_read_b128 v[102:105], v98 offset:49152
	ds_read_b128 v[106:109], v99 offset:32768
	ds_read_b128 v[110:113], v99 offset:36864
	ds_read_b128 v[114:117], v98 offset:53248
	v_mfma_f32_32x32x16_bf16 v[34:49], v[238:241], v[242:245], v[34:49]
	v_lshl_add_u64 v[254:255], v[86:87], 0, s[26:27]
	s_mov_b32 m0, s51
	s_nop 0
	global_load_lds_dwordx4 v[254:255], off
	v_mfma_f32_32x32x16_bf16 v[18:33], v[238:241], v[246:249], v[18:33]
	v_lshl_add_u64 v[254:255], v[88:89], 0, s[26:27]
	s_mov_b32 m0, s83
	s_nop 0
	global_load_lds_dwordx4 v[254:255], off
	v_mfma_f32_32x32x16_bf16 v[50:65], v[250:253], v[242:245], v[50:65]
	v_mfma_f32_32x32x16_bf16 v[2:17], v[250:253], v[246:249], v[2:17]
	s_waitcnt lgkmcnt(0)
	ds_read_b128 v[238:241], v100 offset:49152
	ds_read_b128 v[242:245], v101 offset:32768
	ds_read_b128 v[246:249], v101 offset:36864
	ds_read_b128 v[250:253], v100 offset:53248
	v_mfma_f32_32x32x16_bf16 v[34:49], v[102:105], v[106:109], v[34:49]
	v_lshl_add_u64 v[254:255], v[90:91], 0, s[26:27]
	s_mov_b32 m0, s90
	s_nop 0
	global_load_lds_dwordx4 v[254:255], off
	v_mfma_f32_32x32x16_bf16 v[18:33], v[102:105], v[110:113], v[18:33]
	v_mfma_f32_32x32x16_bf16 v[50:65], v[114:117], v[106:109], v[50:65]
	v_mfma_f32_32x32x16_bf16 v[2:17], v[114:117], v[110:113], v[2:17]
	s_mov_b32 m0, s86
	s_waitcnt vmcnt(0) lgkmcnt(0)
	s_barrier
	ds_read_b128 v[102:105], v74 offset:16384
	ds_read_b128 v[106:109], v96
	ds_read_b128 v[110:113], v96 offset:4096
	ds_read_b128 v[114:117], v74 offset:20480
	v_mfma_f32_32x32x16_bf16 v[34:49], v[238:241], v[242:245], v[34:49]
	v_mfma_f32_32x32x16_bf16 v[18:33], v[238:241], v[246:249], v[18:33]
	v_lshl_add_u64 v[254:255], v[76:77], 0, s[28:29]
	global_load_lds_dwordx4 v[254:255], off
	v_lshl_add_u64 v[254:255], v[78:79], 0, s[28:29]
	s_mov_b32 m0, s87
	s_nop 0
	global_load_lds_dwordx4 v[254:255], off
	v_mfma_f32_32x32x16_bf16 v[50:65], v[250:253], v[242:245], v[50:65]
	v_lshl_add_u64 v[254:255], v[80:81], 0, s[28:29]
	s_mov_b32 m0, s88
	s_nop 0
	global_load_lds_dwordx4 v[254:255], off
	v_mfma_f32_32x32x16_bf16 v[2:17], v[250:253], v[246:249], v[2:17]
	s_waitcnt lgkmcnt(0)
	ds_read_b128 v[238:241], v95 offset:16384
	ds_read_b128 v[242:245], v97
	ds_read_b128 v[246:249], v97 offset:4096
	ds_read_b128 v[250:253], v95 offset:20480
	v_mfma_f32_32x32x16_bf16 v[34:49], v[102:105], v[106:109], v[34:49]
	v_lshl_add_u64 v[254:255], v[82:83], 0, s[28:29]
	s_mov_b32 m0, s89
	s_nop 0
	global_load_lds_dwordx4 v[254:255], off
	v_mfma_f32_32x32x16_bf16 v[18:33], v[102:105], v[110:113], v[18:33]
	v_lshl_add_u64 v[254:255], v[84:85], 0, s[28:29]
	s_mov_b32 m0, s91
	s_nop 0
	global_load_lds_dwordx4 v[254:255], off
	v_mfma_f32_32x32x16_bf16 v[50:65], v[114:117], v[106:109], v[50:65]
	v_mfma_f32_32x32x16_bf16 v[2:17], v[114:117], v[110:113], v[2:17]
	s_waitcnt lgkmcnt(0)
	ds_read_b128 v[102:105], v98 offset:16384
	ds_read_b128 v[106:109], v99
	ds_read_b128 v[110:113], v99 offset:4096
	ds_read_b128 v[114:117], v98 offset:20480
	v_mfma_f32_32x32x16_bf16 v[34:49], v[238:241], v[242:245], v[34:49]
	v_lshl_add_u64 v[254:255], v[86:87], 0, s[28:29]
	s_mov_b32 m0, s92
	s_nop 0
	global_load_lds_dwordx4 v[254:255], off
	v_mfma_f32_32x32x16_bf16 v[18:33], v[238:241], v[246:249], v[18:33]
	v_lshl_add_u64 v[254:255], v[88:89], 0, s[28:29]
	s_mov_b32 m0, s93
	s_nop 0
	global_load_lds_dwordx4 v[254:255], off
	v_mfma_f32_32x32x16_bf16 v[50:65], v[250:253], v[242:245], v[50:65]
	v_mfma_f32_32x32x16_bf16 v[2:17], v[250:253], v[246:249], v[2:17]
	s_waitcnt lgkmcnt(0)
	ds_read_b128 v[238:241], v100 offset:16384
	ds_read_b128 v[242:245], v101
	ds_read_b128 v[246:249], v101 offset:4096
	ds_read_b128 v[250:253], v100 offset:20480
	v_mfma_f32_32x32x16_bf16 v[34:49], v[102:105], v[106:109], v[34:49]
	v_lshl_add_u64 v[254:255], v[90:91], 0, s[28:29]
	s_mov_b32 m0, s94
	s_nop 0
	global_load_lds_dwordx4 v[254:255], off
	v_mfma_f32_32x32x16_bf16 v[18:33], v[102:105], v[110:113], v[18:33]
	v_mfma_f32_32x32x16_bf16 v[50:65], v[114:117], v[106:109], v[50:65]
	v_mfma_f32_32x32x16_bf16 v[2:17], v[114:117], v[110:113], v[2:17]
	s_mov_b32 m0, s1
	s_waitcnt vmcnt(0) lgkmcnt(0)
	s_barrier
; template <class Epi>
; DI void gemm_phase(const u16* __restrict__ A, const u16* __restrict__ B, int mtiles, int ntiles, char* lds, const Epi& epi) {
;     ...
;         for (int kt = 0; kt < 16; ++kt) {
;             if (kt + 1 < 16) GSTAGE((kt + 1) & 1, kt + 1, ga, gb);
;             const char* sa = lds + (kt & 1) * 32768; const char* sb = sa + 16384;
; #pragma unroll
;             for (int ks = 0; ks < 4; ++ks) {
;                 bf16x8 fw[2], fx[2];
; #pragma unroll
;                 for (int ct = 0; ct < 2; ++ct) fw[ct] = *(const bf16x8*)(sb + swz(wn * 64 + ct * 32 + r, 2 * ks + h));
; #pragma unroll
;                 for (int tt = 0; tt < 2; ++tt) fx[tt] = *(const bf16x8*)(sa + swz(wm * 64 + tt * 32 + r, 2 * ks + h));
; #pragma unroll
;                 for (int ct = 0; ct < 2; ++ct)
; #pragma unroll
;                     for (int tt = 0; tt < 2; ++tt) acc[ct][tt] = __builtin_amdgcn_mfma_f32_32x32x16_bf16(fw[ct], fx[tt], acc[ct][tt], 0, 0, 0);
;             }
	ds_read_b128 v[102:105], v74 offset:49152
	ds_read_b128 v[106:109], v96 offset:32768
	ds_read_b128 v[110:113], v96 offset:36864
	ds_read_b128 v[114:117], v74 offset:53248
	v_mfma_f32_32x32x16_bf16 v[34:49], v[238:241], v[242:245], v[34:49]
	v_mfma_f32_32x32x16_bf16 v[18:33], v[238:241], v[246:249], v[18:33]
	v_lshl_add_u64 v[254:255], v[76:77], 0, s[30:31]
	global_load_lds_dwordx4 v[254:255], off
	v_lshl_add_u64 v[254:255], v[78:79], 0, s[30:31]
	s_mov_b32 m0, s7
	s_nop 0
	global_load_lds_dwordx4 v[254:255], off
	v_mfma_f32_32x32x16_bf16 v[50:65], v[250:253], v[242:245], v[50:65]
	v_lshl_add_u64 v[254:255], v[80:81], 0, s[30:31]
	s_mov_b32 m0, s38
	s_nop 0
	global_load_lds_dwordx4 v[254:255], off
	v_mfma_f32_32x32x16_bf16 v[2:17], v[250:253], v[246:249], v[2:17]
	s_waitcnt lgkmcnt(0)
	ds_read_b128 v[238:241], v95 offset:49152
	ds_read_b128 v[242:245], v97 offset:32768
	ds_read_b128 v[246:249], v97 offset:36864
	ds_read_b128 v[250:253], v95 offset:53248
	v_mfma_f32_32x32x16_bf16 v[34:49], v[102:105], v[106:109], v[34:49]
	v_lshl_add_u64 v[254:255], v[82:83], 0, s[30:31]
	s_mov_b32 m0, s39
	s_nop 0
	global_load_lds_dwordx4 v[254:255], off
	v_mfma_f32_32x32x16_bf16 v[18:33], v[102:105], v[110:113], v[18:33]
	v_lshl_add_u64 v[254:255], v[84:85], 0, s[30:31]
	s_mov_b32 m0, s50
	s_nop 0
	global_load_lds_dwordx4 v[254:255], off
	v_mfma_f32_32x32x16_bf16 v[50:65], v[114:117], v[106:109], v[50:65]
	v_mfma_f32_32x32x16_bf16 v[2:17], v[114:117], v[110:113], v[2:17]
	s_waitcnt lgkmcnt(0)
	ds_read_b128 v[102:105], v98 offset:49152
	ds_read_b128 v[106:109], v99 offset:32768
	ds_read_b128 v[110:113], v99 offset:36864
	ds_read_b128 v[114:117], v98 offset:53248
	v_mfma_f32_32x32x16_bf16 v[34:49], v[238:241], v[242:245], v[34:49]
	v_lshl_add_u64 v[254:255], v[86:87], 0, s[30:31]
	s_mov_b32 m0, s51
	s_nop 0
	global_load_lds_dwordx4 v[254:255], off
	v_mfma_f32_32x32x16_bf16 v[18:33], v[238:241], v[246:249], v[18:33]
	v_lshl_add_u64 v[254:255], v[88:89], 0, s[30:31]
	s_mov_b32 m0, s83
	s_nop 0
	global_load_lds_dwordx4 v[254:255], off
	v_mfma_f32_32x32x16_bf16 v[50:65], v[250:253], v[242:245], v[50:65]
	v_mfma_f32_32x32x16_bf16 v[2:17], v[250:253], v[246:249], v[2:17]
	s_waitcnt lgkmcnt(0)
	ds_read_b128 v[238:241], v100 offset:49152
	ds_read_b128 v[242:245], v101 offset:32768
	ds_read_b128 v[246:249], v101 offset:36864
	ds_read_b128 v[250:253], v100 offset:53248
	v_mfma_f32_32x32x16_bf16 v[34:49], v[102:105], v[106:109], v[34:49]
	v_lshl_add_u64 v[254:255], v[90:91], 0, s[30:31]
	s_mov_b32 m0, s90
	s_nop 0
	global_load_lds_dwordx4 v[254:255], off
	v_mfma_f32_32x32x16_bf16 v[18:33], v[102:105], v[110:113], v[18:33]
	v_mfma_f32_32x32x16_bf16 v[50:65], v[114:117], v[106:109], v[50:65]
	v_mfma_f32_32x32x16_bf16 v[2:17], v[114:117], v[110:113], v[2:17]
	s_mov_b32 m0, s86
	s_waitcnt vmcnt(0) lgkmcnt(0)
	s_barrier
	ds_read_b128 v[102:105], v74 offset:16384
	ds_read_b128 v[106:109], v96
	ds_read_b128 v[110:113], v96 offset:4096
	ds_read_b128 v[114:117], v74 offset:20480
	v_mfma_f32_32x32x16_bf16 v[34:49], v[238:241], v[242:245], v[34:49]
	v_mfma_f32_32x32x16_bf16 v[18:33], v[238:241], v[246:249], v[18:33]
	v_lshl_add_u64 v[254:255], v[76:77], 0, s[36:37]
	global_load_lds_dwordx4 v[254:255], off
	v_lshl_add_u64 v[254:255], v[78:79], 0, s[36:37]
	s_mov_b32 m0, s87
	s_nop 0
	global_load_lds_dwordx4 v[254:255], off
	v_mfma_f32_32x32x16_bf16 v[50:65], v[250:253], v[242:245], v[50:65]
	v_lshl_add_u64 v[254:255], v[80:81], 0, s[36:37]
	s_mov_b32 m0, s88
	s_nop 0
	global_load_lds_dwordx4 v[254:255], off
	v_mfma_f32_32x32x16_bf16 v[2:17], v[250:253], v[246:249], v[2:17]
	s_waitcnt lgkmcnt(0)
	ds_read_b128 v[238:241], v95 offset:16384
	ds_read_b128 v[242:245], v97
	ds_read_b128 v[246:249], v97 offset:4096
	ds_read_b128 v[250:253], v95 offset:20480
	v_mfma_f32_32x32x16_bf16 v[34:49], v[102:105], v[106:109], v[34:49]
	v_lshl_add_u64 v[254:255], v[82:83], 0, s[36:37]
	s_mov_b32 m0, s89
	s_nop 0
	global_load_lds_dwordx4 v[254:255], off
	v_mfma_f32_32x32x16_bf16 v[18:33], v[102:105], v[110:113], v[18:33]
	v_lshl_add_u64 v[254:255], v[84:85], 0, s[36:37]
	s_mov_b32 m0, s91
	s_nop 0
	global_load_lds_dwordx4 v[254:255], off
	v_mfma_f32_32x32x16_bf16 v[50:65], v[114:117], v[106:109], v[50:65]
	v_mfma_f32_32x32x16_bf16 v[2:17], v[114:117], v[110:113], v[2:17]
	s_waitcnt lgkmcnt(0)
	ds_read_b128 v[102:105], v98 offset:16384
	ds_read_b128 v[106:109], v99
	ds_read_b128 v[110:113], v99 offset:4096
	ds_read_b128 v[114:117], v98 offset:20480
	v_mfma_f32_32x32x16_bf16 v[34:49], v[238:241], v[242:245], v[34:49]
	v_lshl_add_u64 v[254:255], v[86:87], 0, s[36:37]
	s_mov_b32 m0, s92
	s_nop 0
	global_load_lds_dwordx4 v[254:255], off
	v_mfma_f32_32x32x16_bf16 v[18:33], v[238:241], v[246:249], v[18:33]
	v_lshl_add_u64 v[254:255], v[88:89], 0, s[36:37]
	s_mov_b32 m0, s93
	s_nop 0
	global_load_lds_dwordx4 v[254:255], off
	v_mfma_f32_32x32x16_bf16 v[50:65], v[250:253], v[242:245], v[50:65]
	v_mfma_f32_32x32x16_bf16 v[2:17], v[250:253], v[246:249], v[2:17]
	s_waitcnt lgkmcnt(0)
	ds_read_b128 v[238:241], v100 offset:16384
	ds_read_b128 v[242:245], v101
	ds_read_b128 v[246:249], v101 offset:4096
	ds_read_b128 v[250:253], v100 offset:20480
	v_mfma_f32_32x32x16_bf16 v[34:49], v[102:105], v[106:109], v[34:49]
	v_lshl_add_u64 v[254:255], v[90:91], 0, s[36:37]
	s_mov_b32 m0, s94
	s_nop 0
	global_load_lds_dwordx4 v[254:255], off
	v_mfma_f32_32x32x16_bf16 v[18:33], v[102:105], v[110:113], v[18:33]
	v_mfma_f32_32x32x16_bf16 v[50:65], v[114:117], v[106:109], v[50:65]
	v_mfma_f32_32x32x16_bf16 v[2:17], v[114:117], v[110:113], v[2:17]
	s_mov_b32 m0, s1
	s_waitcnt vmcnt(0) lgkmcnt(0)
	s_barrier
; template <class Epi>
; DI void gemm_phase(const u16* __restrict__ A, const u16* __restrict__ B, int mtiles, int ntiles, char* lds, const Epi& epi) {
;     ...
;         for (int kt = 0; kt < 16; ++kt) {
;             if (kt + 1 < 16) GSTAGE((kt + 1) & 1, kt + 1, ga, gb);
;             const char* sa = lds + (kt & 1) * 32768; const char* sb = sa + 16384;
; #pragma unroll
;             for (int ks = 0; ks < 4; ++ks) {
;                 bf16x8 fw[2], fx[2];
; #pragma unroll
;                 for (int ct = 0; ct < 2; ++ct) fw[ct] = *(const bf16x8*)(sb + swz(wn * 64 + ct * 32 + r, 2 * ks + h));
; #pragma unroll
;                 for (int tt = 0; tt < 2; ++tt) fx[tt] = *(const bf16x8*)(sa + swz(wm * 64 + tt * 32 + r, 2 * ks + h));
; #pragma unroll
;                 for (int ct = 0; ct < 2; ++ct)
; #pragma unroll
;                     for (int tt = 0; tt < 2; ++tt) acc[ct][tt] = __builtin_amdgcn_mfma_f32_32x32x16_bf16(fw[ct], fx[tt], acc[ct][tt], 0, 0, 0);
;             }
	ds_read_b128 v[102:105], v74 offset:49152
	ds_read_b128 v[106:109], v96 offset:32768
	ds_read_b128 v[110:113], v96 offset:36864
	ds_read_b128 v[114:117], v74 offset:53248
	v_mfma_f32_32x32x16_bf16 v[34:49], v[238:241], v[242:245], v[34:49]
	v_mfma_f32_32x32x16_bf16 v[18:33], v[238:241], v[246:249], v[18:33]
	v_lshl_add_u64 v[254:255], v[76:77], 0, s[68:69]
	global_load_lds_dwordx4 v[254:255], off
	v_lshl_add_u64 v[254:255], v[78:79], 0, s[68:69]
	s_mov_b32 m0, s7
	v_lshl_add_u64 v[76:77], v[76:77], 0, s[70:71]
	global_load_lds_dwordx4 v[254:255], off
	v_mfma_f32_32x32x16_bf16 v[50:65], v[250:253], v[242:245], v[50:65]
	v_lshl_add_u64 v[254:255], v[80:81], 0, s[68:69]
	s_mov_b32 m0, s38
	s_nop 0
	global_load_lds_dwordx4 v[254:255], off
	v_mfma_f32_32x32x16_bf16 v[2:17], v[250:253], v[246:249], v[2:17]
	s_waitcnt lgkmcnt(0)
	ds_read_b128 v[238:241], v95 offset:49152
	ds_read_b128 v[242:245], v97 offset:32768
	ds_read_b128 v[246:249], v97 offset:36864
	ds_read_b128 v[250:253], v95 offset:53248
	v_mfma_f32_32x32x16_bf16 v[34:49], v[102:105], v[106:109], v[34:49]
	v_lshl_add_u64 v[254:255], v[82:83], 0, s[68:69]
	s_mov_b32 m0, s39
	s_nop 0
	global_load_lds_dwordx4 v[254:255], off
	v_mfma_f32_32x32x16_bf16 v[18:33], v[102:105], v[110:113], v[18:33]
	v_lshl_add_u64 v[254:255], v[84:85], 0, s[68:69]
	s_mov_b32 m0, s50
	s_nop 0
	global_load_lds_dwordx4 v[254:255], off
	v_mfma_f32_32x32x16_bf16 v[50:65], v[114:117], v[106:109], v[50:65]
	v_mfma_f32_32x32x16_bf16 v[2:17], v[114:117], v[110:113], v[2:17]
	s_waitcnt lgkmcnt(0)
	ds_read_b128 v[102:105], v98 offset:49152
	ds_read_b128 v[106:109], v99 offset:32768
	ds_read_b128 v[110:113], v99 offset:36864
	ds_read_b128 v[114:117], v98 offset:53248
	v_mfma_f32_32x32x16_bf16 v[34:49], v[238:241], v[242:245], v[34:49]
	v_lshl_add_u64 v[254:255], v[86:87], 0, s[68:69]
	s_mov_b32 m0, s51
	s_nop 0
	global_load_lds_dwordx4 v[254:255], off
	v_mfma_f32_32x32x16_bf16 v[18:33], v[238:241], v[246:249], v[18:33]
	v_lshl_add_u64 v[254:255], v[88:89], 0, s[68:69]
	s_mov_b32 m0, s83
	s_nop 0
	global_load_lds_dwordx4 v[254:255], off
	v_mfma_f32_32x32x16_bf16 v[50:65], v[250:253], v[242:245], v[50:65]
	v_mfma_f32_32x32x16_bf16 v[2:17], v[250:253], v[246:249], v[2:17]
	s_waitcnt lgkmcnt(0)
	ds_read_b128 v[238:241], v100 offset:49152
	ds_read_b128 v[242:245], v101 offset:32768
	ds_read_b128 v[246:249], v101 offset:36864
	ds_read_b128 v[250:253], v100 offset:53248
	v_mfma_f32_32x32x16_bf16 v[34:49], v[102:105], v[106:109], v[34:49]
	v_lshl_add_u64 v[254:255], v[90:91], 0, s[68:69]
	s_mov_b32 m0, s90
	s_nop 0
	global_load_lds_dwordx4 v[254:255], off
	v_mfma_f32_32x32x16_bf16 v[18:33], v[102:105], v[110:113], v[18:33]
	v_mfma_f32_32x32x16_bf16 v[50:65], v[114:117], v[106:109], v[50:65]
	v_mfma_f32_32x32x16_bf16 v[2:17], v[114:117], v[110:113], v[2:17]
	s_mov_b32 m0, s86
	s_mov_b32 s86, 0
	s_waitcnt vmcnt(0) lgkmcnt(0)
	s_barrier
	global_load_lds_dwordx4 v[76:77], off
	v_lshl_add_u64 v[76:77], v[78:79], 0, s[70:71]
	s_mov_b32 m0, s87
	v_mfma_f32_32x32x16_bf16 v[34:49], v[238:241], v[242:245], v[34:49]
	global_load_lds_dwordx4 v[76:77], off
	v_lshl_add_u64 v[76:77], v[80:81], 0, s[70:71]
	s_mov_b32 m0, s88
	s_mov_b32 s88, 0
	global_load_lds_dwordx4 v[76:77], off
	v_lshl_add_u64 v[76:77], v[82:83], 0, s[70:71]
	s_mov_b32 m0, s89
	v_mfma_f32_32x32x16_bf16 v[18:33], v[238:241], v[246:249], v[18:33]
	global_load_lds_dwordx4 v[76:77], off
	v_lshl_add_u64 v[76:77], v[84:85], 0, s[70:71]
	s_mov_b32 m0, s91
	s_nop 0
	global_load_lds_dwordx4 v[76:77], off
	v_lshl_add_u64 v[76:77], v[86:87], 0, s[70:71]
	s_mov_b32 m0, s92
	v_mfma_f32_32x32x16_bf16 v[50:65], v[250:253], v[242:245], v[50:65]
	global_load_lds_dwordx4 v[76:77], off
	v_lshl_add_u64 v[76:77], v[88:89], 0, s[70:71]
	s_mov_b32 m0, s93
	s_nop 0
	global_load_lds_dwordx4 v[76:77], off
	v_lshl_add_u64 v[76:77], v[90:91], 0, s[70:71]
	s_mov_b32 m0, s94
	v_mfma_f32_32x32x16_bf16 v[2:17], v[250:253], v[246:249], v[2:17]
	global_load_lds_dwordx4 v[76:77], off
	ds_read_b128 v[76:79], v74 offset:16384
	ds_read_b128 v[80:83], v96
	ds_read_b128 v[84:87], v96 offset:4096
	ds_read_b128 v[88:91], v74 offset:20480
	s_waitcnt lgkmcnt(0)
	v_mfma_f32_32x32x16_bf16 v[34:49], v[76:79], v[80:83], v[34:49]
	v_mfma_f32_32x32x16_bf16 v[18:33], v[76:79], v[84:87], v[18:33]
	v_mfma_f32_32x32x16_bf16 v[50:65], v[88:91], v[80:83], v[50:65]
	v_mfma_f32_32x32x16_bf16 v[2:17], v[88:91], v[84:87], v[2:17]
	ds_read_b128 v[76:79], v95 offset:16384
	ds_read_b128 v[80:83], v97
	ds_read_b128 v[84:87], v97 offset:4096
	ds_read_b128 v[88:91], v95 offset:20480
	s_waitcnt lgkmcnt(0)
	v_mfma_f32_32x32x16_bf16 v[34:49], v[76:79], v[80:83], v[34:49]
	v_mfma_f32_32x32x16_bf16 v[18:33], v[76:79], v[84:87], v[18:33]
	v_mfma_f32_32x32x16_bf16 v[50:65], v[88:91], v[80:83], v[50:65]
	v_mfma_f32_32x32x16_bf16 v[2:17], v[88:91], v[84:87], v[2:17]
	ds_read_b128 v[76:79], v98 offset:16384
	ds_read_b128 v[80:83], v99
	ds_read_b128 v[84:87], v99 offset:4096
	ds_read_b128 v[88:91], v98 offset:20480
	s_waitcnt lgkmcnt(0)
	v_mfma_f32_32x32x16_bf16 v[34:49], v[76:79], v[80:83], v[34:49]
	v_mfma_f32_32x32x16_bf16 v[18:33], v[76:79], v[84:87], v[18:33]
	v_mfma_f32_32x32x16_bf16 v[50:65], v[88:91], v[80:83], v[50:65]
	v_mfma_f32_32x32x16_bf16 v[2:17], v[88:91], v[84:87], v[2:17]
	ds_read_b128 v[76:79], v100 offset:16384
	ds_read_b128 v[80:83], v101
	ds_read_b128 v[84:87], v101 offset:4096
	ds_read_b128 v[88:91], v100 offset:20480
	s_waitcnt vmcnt(0) lgkmcnt(0)
	s_barrier
; #define TILE_MN(t, M0, N0) do { int pan_ = (t) / (mtiles * 8); if (pan_ >= npan) pan_ = npan - 1; const int pw_ = (pan_ == npan - 1) ? ntiles - 8 * pan_ : 8; const int loc_ = (t) - pan_ * mtiles * 8; \
;         M0 = (loc_ / pw_) * 128; N0 = (8 * pan_ + loc_ % pw_) * 128; } while (0)
; template <class Epi>
; DI void gemm_phase(const u16* __restrict__ A, const u16* __restrict__ B, int mtiles, int ntiles, char* lds, const Epi& epi) {
;     ...
;         for (int kt = 0; kt < 16; ++kt) {
;             if (kt + 1 < 16) GSTAGE((kt + 1) & 1, kt + 1, ga, gb);
;             const char* sa = lds + (kt & 1) * 32768; const char* sb = sa + 16384;
; #pragma unroll
;             for (int ks = 0; ks < 4; ++ks) {
;                 bf16x8 fw[2], fx[2];
; #pragma unroll
;                 for (int ct = 0; ct < 2; ++ct) fw[ct] = *(const bf16x8*)(sb + swz(wn * 64 + ct * 32 + r, 2 * ks + h));
; #pragma unroll
;                 for (int tt = 0; tt < 2; ++tt) fx[tt] = *(const bf16x8*)(sa + swz(wm * 64 + tt * 32 + r, 2 * ks + h));
; #pragma unroll
;                 for (int ct = 0; ct < 2; ++ct)
; #pragma unroll
;                     for (int tt = 0; tt < 2; ++tt) acc[ct][tt] = __builtin_amdgcn_mfma_f32_32x32x16_bf16(fw[ct], fx[tt], acc[ct][tt], 0, 0, 0);
;             }
;             __syncthreads();
;         }
;         const int nxt = tile + (int)gridDim.x; int m1 = 0, n1 = 0;
;         if (nxt < ntile) { TILE_MN(nxt, m1, n1); GSTAGE(0, 0, A + (size_t)m1 * 1024, B + (size_t)n1 * 1024); }
	v_mfma_f32_32x32x16_bf16 v[34:49], v[76:79], v[80:83], v[34:49]
	v_mfma_f32_32x32x16_bf16 v[18:33], v[76:79], v[84:87], v[18:33]
	v_mfma_f32_32x32x16_bf16 v[50:65], v[88:91], v[80:83], v[50:65]
	v_mfma_f32_32x32x16_bf16 v[2:17], v[88:91], v[84:87], v[2:17]
	ds_read_b128 v[76:79], v96 offset:32768
	ds_read_b128 v[80:83], v96 offset:36864
	ds_read_b128 v[84:87], v74 offset:49152
	ds_read_b128 v[88:91], v74 offset:53248
	s_waitcnt lgkmcnt(1)
	v_mfma_f32_32x32x16_bf16 v[34:49], v[84:87], v[76:79], v[34:49]
	v_mfma_f32_32x32x16_bf16 v[18:33], v[84:87], v[80:83], v[18:33]
	s_waitcnt lgkmcnt(0)
	v_mfma_f32_32x32x16_bf16 v[50:65], v[88:91], v[76:79], v[50:65]
	v_mfma_f32_32x32x16_bf16 v[2:17], v[88:91], v[80:83], v[2:17]
	ds_read_b128 v[76:79], v95 offset:49152
	ds_read_b128 v[80:83], v97 offset:32768
	ds_read_b128 v[84:87], v97 offset:36864
	ds_read_b128 v[88:91], v95 offset:53248
	s_waitcnt lgkmcnt(2)
	v_mfma_f32_32x32x16_bf16 v[34:49], v[76:79], v[80:83], v[34:49]
	s_waitcnt lgkmcnt(1)
	v_mfma_f32_32x32x16_bf16 v[18:33], v[76:79], v[84:87], v[18:33]
	s_waitcnt lgkmcnt(0)
	v_mfma_f32_32x32x16_bf16 v[50:65], v[88:91], v[80:83], v[50:65]
	v_mfma_f32_32x32x16_bf16 v[2:17], v[88:91], v[84:87], v[2:17]
	ds_read_b128 v[76:79], v98 offset:49152
	ds_read_b128 v[80:83], v99 offset:32768
	ds_read_b128 v[84:87], v99 offset:36864
	ds_read_b128 v[88:91], v98 offset:53248
	s_waitcnt lgkmcnt(2)
	v_mfma_f32_32x32x16_bf16 v[34:49], v[76:79], v[80:83], v[34:49]
	s_waitcnt lgkmcnt(1)
	v_mfma_f32_32x32x16_bf16 v[18:33], v[76:79], v[84:87], v[18:33]
	s_waitcnt lgkmcnt(0)
	v_mfma_f32_32x32x16_bf16 v[50:65], v[88:91], v[80:83], v[50:65]
	v_mfma_f32_32x32x16_bf16 v[2:17], v[88:91], v[84:87], v[2:17]
	ds_read_b128 v[76:79], v100 offset:49152
	ds_read_b128 v[80:83], v101 offset:32768
	ds_read_b128 v[84:87], v101 offset:36864
	ds_read_b128 v[88:91], v100 offset:53248
	s_waitcnt lgkmcnt(0)
	s_barrier
	v_mfma_f32_32x32x16_bf16 v[34:49], v[76:79], v[80:83], v[34:49]
	v_mfma_f32_32x32x16_bf16 v[18:33], v[76:79], v[84:87], v[18:33]
	v_mfma_f32_32x32x16_bf16 v[50:65], v[88:91], v[80:83], v[50:65]
	v_mfma_f32_32x32x16_bf16 v[2:17], v[88:91], v[84:87], v[2:17]
	s_cbranch_scc1 .LBB0_99
	s_mov_b32 m0, s1
	s_mul_hi_i32 s1, s33, 0x3e0f83e1
	s_lshr_b32 s86, s1, 31
	s_ashr_i32 s1, s1, 8
	s_add_i32 s1, s1, s86
	s_cmpk_lt_i32 s33, 0x1080
	s_cselect_b32 s1, s1, 3
	s_cmp_eq_u32 s1, 3
	s_cselect_b32 s87, 9, 8
	v_cvt_f32_ubyte0_e32 v74, s87
	v_rcp_iflag_f32_e32 v74, v74
	s_sub_i32 s91, 0, s87
	s_mul_i32 s86, s1, 0xfffffbe0
	s_add_i32 s88, s33, s86
	v_mul_f32_e32 v74, 0x4f7ffffe, v74
	v_cvt_u32_f32_e32 v74, v74
	s_abs_i32 s89, s88
	s_ashr_i32 s86, s88, 31
	v_readfirstlane_b32 s92, v74
	s_mul_i32 s91, s91, s92
	s_mul_hi_u32 s91, s92, s91
	s_add_i32 s92, s92, s91
	s_mul_hi_u32 s91, s89, s92
	s_mul_i32 s92, s91, s87
	s_sub_i32 s89, s89, s92
	s_add_i32 s92, s91, 1
	s_sub_i32 s93, s89, s87
	s_cmp_ge_u32 s89, s87
	s_cselect_b32 s91, s92, s91
	s_cselect_b32 s89, s93, s89
	s_add_i32 s92, s91, 1
	s_cmp_ge_u32 s89, s87
	s_cselect_b32 s89, s92, s91
	s_xor_b32 s89, s89, s86
	s_sub_i32 s89, s89, s86
	s_lshl_b32 s86, s89, 7
	s_mul_i32 s89, s89, s87
	s_sub_i32 s87, s88, s89
	s_lshl_b32 s1, s1, 10
	s_lshl_b32 s87, s87, 7
	s_add_i32 s88, s87, s1
	s_ashr_i32 s87, s86, 31
	s_lshl_b64 s[92:93], s[86:87], 11
	s_add_u32 s92, s54, s92
	s_addc_u32 s93, s55, s93
	s_ashr_i32 s89, s88, 31
	s_lshl_b64 s[94:95], s[88:89], 11
	v_readlane_b32 s1, v236, 9
	s_add_u32 s94, s1, s94
	v_readlane_b32 s1, v236, 11
	s_addc_u32 s95, s1, s95
	v_lshl_add_u64 v[76:77], s[92:93], 0, v[66:67]
	global_load_lds_dwordx4 v[76:77], off
	v_lshl_add_u64 v[66:67], s[94:95], 0, v[66:67]
	s_mov_b32 m0, s7
	s_nop 0
	global_load_lds_dwordx4 v[66:67], off
	v_lshl_add_u64 v[66:67], s[92:93], 0, v[68:69]
	s_mov_b32 m0, s38
	s_nop 0
	global_load_lds_dwordx4 v[66:67], off
	v_lshl_add_u64 v[66:67], s[94:95], 0, v[68:69]
	s_mov_b32 m0, s39
	s_nop 0
	global_load_lds_dwordx4 v[66:67], off
	v_lshl_add_u64 v[66:67], s[92:93], 0, v[70:71]
	s_mov_b32 m0, s50
	s_nop 0
	global_load_lds_dwordx4 v[66:67], off
	v_lshl_add_u64 v[66:67], s[94:95], 0, v[70:71]
	s_mov_b32 m0, s51
	s_nop 0
	global_load_lds_dwordx4 v[66:67], off
	v_lshl_add_u64 v[66:67], s[92:93], 0, v[72:73]
	s_mov_b32 m0, s83
	s_nop 0
	global_load_lds_dwordx4 v[66:67], off
	v_lshl_add_u64 v[66:67], s[94:95], 0, v[72:73]
	s_mov_b32 m0, s90
	s_nop 0
	global_load_lds_dwordx4 v[66:67], off

; DI unsigned xb_add(unsigned* p, unsigned v) { return __hip_atomic_fetch_add(p, v, __ATOMIC_RELAXED, __HIP_MEMORY_SCOPE_AGENT); }
; DI void xcd_barrier(const XcdBarrier& b) {
;     ...
;         const unsigned old = xb_add(&bar[XB_XSUB(b.x)], 1u);
;         const unsigned gen = old / nloc;
;         if (old + 1u == (gen + 1u) * nloc) {
;             __builtin_amdgcn_fence(__ATOMIC_RELEASE, "agent");
.LBB0_162:
	s_or_b64 exec, exec, s[6:7]
	v_cvt_f32_u32_e32 v6, v4
	s_waitcnt vmcnt(0)
	v_readfirstlane_b32 s2, v5
	s_and_b32 s96, s2, 63
	s_cmp_lg_u32 s96, 28
	s_cbranch_scc1 .Lbw_1_0
	buffer_wbl2 sc1

; DI unsigned xb_add(unsigned* p, unsigned v) { return __hip_atomic_fetch_add(p, v, __ATOMIC_RELAXED, __HIP_MEMORY_SCOPE_AGENT); }
; DI void xcd_barrier(const XcdBarrier& b) {
;     ...
;         const unsigned old = xb_add(&bar[XB_XSUB(b.x)], 1u);
;         const unsigned gen = old / nloc;
;         if (old + 1u == (gen + 1u) * nloc) {
;             __builtin_amdgcn_fence(__ATOMIC_RELEASE, "agent");
.LBB0_541:
	s_or_b64 exec, exec, s[6:7]
	v_cvt_f32_u32_e32 v5, v3
	s_waitcnt vmcnt(0)
	v_readfirstlane_b32 s4, v4
	s_and_b32 s96, s4, 63
	s_cmp_lg_u32 s96, 28
	s_cbranch_scc1 .Lbw_4_0
	buffer_wbl2 sc1
